# counted waits: final RMSNorm loop waits for row A's six loads (vmcnt 6), processes and stores row A, then waits for row B's loads (vmcnt 4) instead of one vmcnt(0)
# baseline (speedup 1.0000x reference)
; #define GAS __attribute__((address_space(1)))
; __device__ __forceinline__ float bflo(unsigned w) { return __uint_as_float(w << 16); }
; __device__ __forceinline__ float bfhi(unsigned w) { return __uint_as_float(w & 0xffff0000u); }
; __global__ void __launch_bounds__(NWAVES * 64, 2) mk_fwd(Args args) {
;     ...
;         for (int m = fbase; m < fend; m += fstep) {
;             const int m1 = (m + fsec < fend) ? m + fsec : m;
;             const v4u a0 = *(const GAS v4u*)(HB + (size_t)m * DM + 8 * lane), a1 = *(const GAS v4u*)(HB + (size_t)m * DM + 512 + 8 * lane);
;             const v4u b0 = *(const GAS v4u*)(HB + (size_t)m1 * DM + 8 * lane), b1 = *(const GAS v4u*)(HB + (size_t)m1 * DM + 512 + 8 * lane);
;             const float rs0 = rsqrtf(pg8::row_ssq(sq, 16, m, SSQ_PS(2 * DEPTH)) * (1.0f / 1024.0f) + pg8::RMS_EPS), rs1 = rsqrtf(pg8::row_ssq(sq, 16, m1, SSQ_PS(2 * DEPTH)) * (1.0f / 1024.0f) + pg8::RMS_EPS);
;             GAS f32x4* o0 = (GAS f32x4*)(out + (size_t)m * DM + 8 * lane); GAS f32x4* o1 = (GAS f32x4*)(out + (size_t)m1 * DM + 8 * lane);
;             o0[0] = (f32x4){bflo(a0.x), bfhi(a0.x), bflo(a0.y), bfhi(a0.y)} * rs0 * gv[0]; o0[1] = (f32x4){bflo(a0.z), bfhi(a0.z), bflo(a0.w), bfhi(a0.w)} * rs0 * gv[1];
;             o0[128] = (f32x4){bflo(a1.x), bfhi(a1.x), bflo(a1.y), bfhi(a1.y)} * rs0 * gv[2]; o0[129] = (f32x4){bflo(a1.z), bfhi(a1.z), bflo(a1.w), bfhi(a1.w)} * rs0 * gv[3];
;             if (m1 != m) {
;                 o1[0] = (f32x4){bflo(b0.x), bfhi(b0.x), bflo(b0.y), bfhi(b0.y)} * rs1 * gv[0]; o1[1] = (f32x4){bflo(b0.z), bfhi(b0.z), bflo(b0.w), bfhi(b0.w)} * rs1 * gv[1];
;                 o1[128] = (f32x4){bflo(b1.x), bfhi(b1.x), bflo(b1.y), bfhi(b1.y)} * rs1 * gv[2]; o1[129] = (f32x4){bflo(b1.z), bfhi(b1.z), bflo(b1.w), bfhi(b1.w)} * rs1 * gv[3];
;             }
;         }
.LBB0_1074:
	s_add_i32 s6, s18, s16
	s_cmp_lt_i32 s6, s8
	s_cselect_b32 s6, s6, s16
	s_ashr_i32 s14, s16, 8
	s_ashr_i32 s7, s6, 31
	s_ashr_i32 s15, s14, 31
	s_lshl_b64 s[12:13], s[6:7], 11
	s_lshl_b64 s[14:15], s[14:15], 14
	v_readlane_b32 s17, v241, 25
	s_add_u32 s14, s17, s14
	v_readlane_b32 s19, v241, 26
	s_addc_u32 s15, s19, s15
	s_and_b32 s11, s9, 0xff0
	s_lshl_b32 s11, s11, 2
	v_mov_b32_e32 v18, s11
	global_load_dwordx4 v[50:53], v[44:45], off
	global_load_dwordx4 v[54:57], v[44:45], off offset:1024
	global_load_dwordx4 v[58:61], v18, s[14:15]
	global_load_dwordx4 v[62:65], v18, s[14:15] offset:32
	global_load_dwordx4 v[66:69], v18, s[14:15] offset:16
	global_load_dwordx4 v[70:73], v18, s[14:15] offset:48
	v_lshl_add_u64 v[26:27], v[42:43], 0, s[12:13]
	s_ashr_i32 s12, s6, 8
	s_ashr_i32 s13, s12, 31
	s_lshl_b64 s[12:13], s[12:13], 14
	s_add_u32 s12, s17, s12
	s_addc_u32 s13, s19, s13
	s_lshl_b32 s11, s6, 6
	s_and_b32 s11, s11, 0x3fc0
	v_mov_b32_e32 v49, s11
	global_load_dwordx4 v[22:25], v[26:27], off
	global_load_dwordx4 v[18:21], v[26:27], off offset:1024
	s_nop 0
	global_load_dwordx4 v[26:29], v49, s[12:13] offset:48
	global_load_dwordx4 v[34:37], v49, s[12:13] offset:32
	global_load_dwordx4 v[30:33], v49, s[12:13] offset:16
	global_load_dwordx4 v[38:41], v49, s[12:13]
	s_cmp_eq_u32 s16, s6
	s_waitcnt vmcnt(6)
	v_mov_b32_e32 v82, v58
	v_mov_b32_e32 v83, v62
	v_mov_b32_e32 v62, v59
	v_mov_b32_e32 v58, v60
	v_mov_b32_e32 v59, v64
	v_mov_b32_e32 v64, v61
	v_mov_b32_e32 v60, v66
	v_mov_b32_e32 v61, v70
	v_mov_b32_e32 v70, v67
	v_mov_b32_e32 v66, v68
	v_mov_b32_e32 v67, v72
	v_mov_b32_e32 v72, v69
	v_pk_add_f32 v[62:63], v[82:83], v[62:63]
	v_pk_add_f32 v[58:59], v[58:59], v[64:65]
	v_pk_add_f32 v[60:61], v[60:61], v[70:71]
	v_pk_add_f32 v[64:65], v[66:67], v[72:73]
	v_pk_add_f32 v[58:59], v[62:63], v[58:59]
	v_pk_add_f32 v[60:61], v[60:61], v[64:65]
	v_lshlrev_b32_e32 v74, 16, v50
	v_pk_add_f32 v[58:59], v[58:59], v[60:61]
	v_and_b32_e32 v75, 0xffff0000, v50
	v_add_f32_e32 v49, v58, v59
	v_fmamk_f32 v49, v49, 0x3a800000, v48
	v_mul_f32_e32 v58, 0x4b800000, v49
	v_cmp_gt_f32_e32 vcc, s1, v49
	v_lshlrev_b32_e32 v50, 16, v51
	v_and_b32_e32 v51, 0xffff0000, v51
	v_cndmask_b32_e32 v49, v49, v58, vcc
	v_rsq_f32_e32 v49, v49
	v_lshlrev_b32_e32 v76, 16, v52
	v_and_b32_e32 v77, 0xffff0000, v52
	v_lshlrev_b32_e32 v52, 16, v53
	v_mul_f32_e32 v58, 0x45800000, v49
	v_cndmask_b32_e32 v58, v49, v58, vcc
	v_and_b32_e32 v53, 0xffff0000, v53
	v_lshlrev_b32_e32 v78, 16, v54
	v_and_b32_e32 v79, 0xffff0000, v54
	v_lshlrev_b32_e32 v54, 16, v55
	v_and_b32_e32 v55, 0xffff0000, v55
	v_lshlrev_b32_e32 v80, 16, v56
	v_and_b32_e32 v81, 0xffff0000, v56
	v_lshlrev_b32_e32 v56, 16, v57
	v_and_b32_e32 v57, 0xffff0000, v57
	v_pk_mul_f32 v[60:61], v[58:59], v[74:75] op_sel_hi:[0,1]
	v_pk_mul_f32 v[50:51], v[58:59], v[50:51] op_sel_hi:[0,1]
	v_pk_mul_f32 v[62:63], v[58:59], v[76:77] op_sel_hi:[0,1]
	v_pk_mul_f32 v[64:65], v[58:59], v[52:53] op_sel_hi:[0,1]
	v_pk_mul_f32 v[66:67], v[58:59], v[78:79] op_sel_hi:[0,1]
	v_pk_mul_f32 v[68:69], v[58:59], v[54:55] op_sel_hi:[0,1]
	v_pk_mul_f32 v[70:71], v[58:59], v[80:81] op_sel_hi:[0,1]
	v_pk_mul_f32 v[72:73], v[58:59], v[56:57] op_sel_hi:[0,1]
	v_pk_mul_f32 v[52:53], v[8:9], v[50:51]
	v_pk_mul_f32 v[50:51], v[6:7], v[60:61]
	v_pk_mul_f32 v[56:57], v[4:5], v[64:65]
	v_pk_mul_f32 v[54:55], v[2:3], v[62:63]
	v_pk_mul_f32 v[60:61], v[16:17], v[68:69]
	v_pk_mul_f32 v[58:59], v[14:15], v[66:67]
	v_pk_mul_f32 v[64:65], v[12:13], v[72:73]
	v_pk_mul_f32 v[62:63], v[10:11], v[70:71]
	global_store_dwordx4 v[46:47], v[50:53], off
	global_store_dwordx4 v[46:47], v[54:57], off offset:16
	global_store_dwordx4 v[46:47], v[58:61], off offset:2048
	global_store_dwordx4 v[46:47], v[62:65], off offset:2064
	s_cbranch_scc1 .Lfin_early
	s_waitcnt vmcnt(4)
	v_mov_b32_e32 v50, v38
	v_mov_b32_e32 v51, v34
	v_mov_b32_e32 v34, v39
	v_mov_b32_e32 v38, v40
	v_mov_b32_e32 v39, v36
	v_mov_b32_e32 v36, v41
	v_pk_add_f32 v[34:35], v[50:51], v[34:35]
	v_pk_add_f32 v[36:37], v[38:39], v[36:37]
	s_lshl_b64 s[6:7], s[6:7], 10
	v_pk_add_f32 v[34:35], v[34:35], v[36:37]
	v_mov_b32_e32 v36, v30
	v_mov_b32_e32 v37, v26
	v_mov_b32_e32 v26, v31
	v_mov_b32_e32 v30, v32
	v_mov_b32_e32 v31, v28
	v_mov_b32_e32 v28, v33
	v_pk_add_f32 v[26:27], v[36:37], v[26:27]
	v_pk_add_f32 v[28:29], v[30:31], v[28:29]
	v_lshl_add_u64 v[32:33], s[6:7], 2, v[0:1]
	v_pk_add_f32 v[26:27], v[26:27], v[28:29]
	s_nop 0
	v_pk_add_f32 v[26:27], v[34:35], v[26:27]
	s_nop 0
	v_add_f32_e32 v26, v26, v27
	v_fmamk_f32 v26, v26, 0x3a800000, v48
	v_mul_f32_e32 v27, 0x4b800000, v26
	v_cmp_gt_f32_e32 vcc, s1, v26
	s_nop 1
	v_cndmask_b32_e32 v26, v26, v27, vcc
	v_rsq_f32_e32 v26, v26
	s_nop 0
	v_mul_f32_e32 v27, 0x45800000, v26
	v_cndmask_b32_e32 v30, v26, v27, vcc
	v_lshlrev_b32_e32 v26, 16, v22
	v_and_b32_e32 v27, 0xffff0000, v22
	v_lshlrev_b32_e32 v22, 16, v23
	v_and_b32_e32 v23, 0xffff0000, v23
	v_pk_mul_f32 v[22:23], v[30:31], v[22:23] op_sel_hi:[0,1]
	v_pk_mul_f32 v[28:29], v[8:9], v[22:23]
	v_lshlrev_b32_e32 v22, 16, v24
	v_and_b32_e32 v23, 0xffff0000, v24
	v_lshlrev_b32_e32 v24, 16, v25
	v_and_b32_e32 v25, 0xffff0000, v25
	v_pk_mul_f32 v[22:23], v[30:31], v[22:23] op_sel_hi:[0,1]
	v_pk_mul_f32 v[24:25], v[30:31], v[24:25] op_sel_hi:[0,1]
	v_pk_mul_f32 v[24:25], v[4:5], v[24:25]
	v_pk_mul_f32 v[22:23], v[2:3], v[22:23]
	global_store_dwordx4 v[32:33], v[22:25], off offset:16
	v_pk_mul_f32 v[26:27], v[30:31], v[26:27] op_sel_hi:[0,1]
	v_pk_mul_f32 v[26:27], v[6:7], v[26:27]
	v_lshlrev_b32_e32 v22, 16, v18
	v_and_b32_e32 v23, 0xffff0000, v18
	v_lshlrev_b32_e32 v18, 16, v19
	v_and_b32_e32 v19, 0xffff0000, v19
	v_pk_mul_f32 v[18:19], v[30:31], v[18:19] op_sel_hi:[0,1]
	v_pk_mul_f32 v[24:25], v[16:17], v[18:19]
	v_lshlrev_b32_e32 v18, 16, v20
	v_and_b32_e32 v19, 0xffff0000, v20
	v_lshlrev_b32_e32 v20, 16, v21
	v_and_b32_e32 v21, 0xffff0000, v21
	v_pk_mul_f32 v[22:23], v[30:31], v[22:23] op_sel_hi:[0,1]
	v_pk_mul_f32 v[18:19], v[30:31], v[18:19] op_sel_hi:[0,1]
	v_pk_mul_f32 v[20:21], v[30:31], v[20:21] op_sel_hi:[0,1]
	v_pk_mul_f32 v[22:23], v[14:15], v[22:23]
	v_pk_mul_f32 v[20:21], v[12:13], v[20:21]
	v_pk_mul_f32 v[18:19], v[10:11], v[18:19]
	global_store_dwordx4 v[32:33], v[26:29], off
	global_store_dwordx4 v[32:33], v[22:25], off offset:2048
	global_store_dwordx4 v[32:33], v[18:21], off offset:2064
	s_branch .LBB0_1073
.Lfin_early:
	s_waitcnt vmcnt(0)
	s_branch .LBB0_1073
.LBB0_1076:
	s_endpgm
